# group-norm phase: the leftover per-element bonus-scalar products (inputs no longer loaded) removed from the row loop (96 VALU -> s_nop 0)
# baseline (speedup 1.0000x reference)
; __device__ __forceinline__ void unpack8(const u32x4 w, f32x4& a, f32x4& b) { a = (f32x4){bflo(w.x), bfhi(w.x), bflo(w.y), bfhi(w.y)}; b = (f32x4){bflo(w.z), bfhi(w.z), bflo(w.w), bfhi(w.w)}; }
; __device__ __forceinline__ void gn_phase(bf16_t* Y, const bf16_t* R, const bf16_t* Kb, const bf16_t* V, const bf16_t* Z, const bf16_t* WA, const float* k_a, const float* r_k, const float* gn_g, const float* gn_b, int G, int bid, int tid) {
;     ...
;     for (int m = gw; m < M; m += NGW) {
;         const size_t off = (size_t)m * D + col;
;         f32x4 y[4], r[4], k[4], v[4], z[4], aa[4];
; #pragma unroll
;         for (int j = 0; j < 2; ++j) { unpack8(ry_[j], y[2 * j], y[2 * j + 1]); unpack8(rr_[j], r[2 * j], r[2 * j + 1]); unpack8(rk_[j], k[2 * j], k[2 * j + 1]);
;             unpack8(rv_[j], v[2 * j], v[2 * j + 1]); unpack8(rz_[j], z[2 * j], z[2 * j + 1]); unpack8(ra_[j], aa[2 * j], aa[2 * j + 1]); }
;         if (m + NGW < M) GN_LOAD(m + NGW);
;         float s = 0.f, bs = 0.f;
; #pragma unroll
;         for (int q = 0; q < 4; ++q) {
;             s += (y[q].x + y[q].y) + (y[q].z + y[q].w);
;             const f32x4 kp = k[q] * (1.0f + (aa[q] - 1.0f) * kaq[q]);
;             const f32x4 t = r[q] * kp * rkq[q];
;             bs += (t.x + t.y) + (t.z + t.w);
;         }
;         s += __shfl_xor(s, 1); s += __shfl_xor(s, 2); bs += __shfl_xor(bs, 1); bs += __shfl_xor(bs, 2);
;         const float mean = s * (1.0f / 64.0f);
;         float q2 = 0.f;
; #pragma unroll
;         for (int q = 0; q < 4; ++q) { const f32x4 dlt = y[q] - mean; q2 += (dlt.x * dlt.x + dlt.y * dlt.y) + (dlt.z * dlt.z + dlt.w * dlt.w); }
;         q2 += __shfl_xor(q2, 1); q2 += __shfl_xor(q2, 2);
;         const float rstd = 1.0f / sqrtf(q2 * (1.0f / 64.0f) + 64e-5f);
.LBB0_1009:
	s_nop 0
	s_nop 0
	s_nop 0
	s_nop 0
	s_nop 0
	s_nop 0
	s_nop 0
	s_nop 0
	s_nop 0
	s_nop 0
	s_nop 0
	s_nop 0
	s_nop 0
	s_nop 0
	s_nop 0
	s_nop 0
	s_nop 0
	s_nop 0
	s_nop 0
	s_nop 0
	s_nop 0
	s_nop 0
	s_nop 0
	s_nop 0
	s_nop 0
	s_nop 0
	s_nop 0
	s_nop 0
	s_nop 0
	s_nop 0
	s_nop 0
	v_lshlrev_b32_e32 v177, 16, v157
	v_lshlrev_b32_e32 v176, 16, v156
	v_and_b32_e32 v175, 0xffff0000, v157
	v_and_b32_e32 v174, 0xffff0000, v156
	v_lshlrev_b32_e32 v169, 16, v159
	v_lshlrev_b32_e32 v168, 16, v158
	v_and_b32_e32 v157, 0xffff0000, v159
	v_and_b32_e32 v156, 0xffff0000, v158
	s_nop 0
	s_nop 0
	s_nop 0
	s_nop 0
	s_nop 0
	s_nop 0
	s_nop 0
	s_nop 0
	s_nop 0
	s_nop 0
	v_pk_add_f32 v[224:225], v[176:177], v[174:175]
	v_pk_add_f32 v[188:189], v[168:169], v[156:157]
	s_nop 0
	s_nop 0
	v_lshlrev_b32_e32 v172, 16, v144
	v_and_b32_e32 v170, 0xffff0000, v144
	v_lshlrev_b32_e32 v158, 16, v145
	v_and_b32_e32 v154, 0xffff0000, v145
	v_lshlrev_b32_e32 v144, 16, v140
	v_and_b32_e32 v145, 0xffff0000, v140
	v_lshlrev_b32_e32 v140, 16, v141
	v_and_b32_e32 v141, 0xffff0000, v141
	v_add_f32_e32 v129, v224, v225
	s_nop 0
	v_pk_add_f32 v[188:189], v[188:189], v[188:189] op_sel_hi:[0,1]
	s_nop 0
	s_nop 0
	v_lshlrev_b32_e32 v152, 16, v146
	v_and_b32_e32 v150, 0xffff0000, v146
	v_lshlrev_b32_e32 v166, 16, v147
	v_and_b32_e32 v146, 0xffff0000, v147
	v_lshlrev_b32_e32 v147, 16, v136
	v_and_b32_e32 v149, 0xffff0000, v136
	v_lshlrev_b32_e32 v185, 16, v137
	v_and_b32_e32 v226, 0xffff0000, v137
	v_lshlrev_b32_e32 v227, 16, v138
	v_and_b32_e32 v228, 0xffff0000, v138
	v_lshlrev_b32_e32 v229, 16, v139
	v_and_b32_e32 v230, 0xffff0000, v139
	v_lshlrev_b32_e32 v138, 16, v142
	v_and_b32_e32 v136, 0xffff0000, v142
	v_lshlrev_b32_e32 v130, 16, v143
	v_and_b32_e32 v128, 0xffff0000, v143
	v_add_f32_e32 v129, 0, v129
	s_nop 0
	s_nop 0
	s_nop 0
	v_add_f32_e32 v139, v144, v145
	v_add_f32_e32 v137, v140, v141
	v_mov_b32_e32 v131, v189
	s_nop 0
	s_nop 0
	v_pk_add_f32 v[192:193], v[138:139], v[136:137]
	v_pk_add_f32 v[188:189], v[130:131], v[128:129]
	s_nop 0
	v_pk_add_f32 v[188:189], v[192:193], v[188:189]
	s_nop 0
	v_lshlrev_b32_e32 v212, 16, v133
	v_and_b32_e32 v213, 0xffff0000, v133
	s_nop 0
	s_nop 0
	s_nop 0
	s_nop 0
	v_lshlrev_b32_e32 v216, 16, v125
	v_and_b32_e32 v217, 0xffff0000, v125
	s_nop 0
	s_nop 0
	s_nop 0
	s_nop 0
	v_lshlrev_b32_e32 v148, 16, v120
	v_and_b32_e32 v142, 0xffff0000, v120
	v_lshlrev_b32_e32 v134, 16, v121
	v_and_b32_e32 v132, 0xffff0000, v121
	v_lshlrev_b32_e32 v126, 16, v122
	v_and_b32_e32 v124, 0xffff0000, v122
	v_lshlrev_b32_e32 v122, 16, v123
	v_and_b32_e32 v120, 0xffff0000, v123
	v_lshlrev_b32_e32 v127, 16, v116
	v_and_b32_e32 v133, 0xffff0000, v116
	v_lshlrev_b32_e32 v125, 16, v117
	v_and_b32_e32 v123, 0xffff0000, v117
	v_lshlrev_b32_e32 v121, 16, v118
	v_and_b32_e32 v117, 0xffff0000, v118
	v_lshlrev_b32_e32 v116, 16, v119
	v_and_b32_e32 v22, 0xffff0000, v119
	s_nop 0
	s_nop 0
	v_lshlrev_b32_e32 v112, 16, v113
	v_and_b32_e32 v113, 0xffff0000, v113
	v_add_f32_e32 v129, v188, v189
	v_pk_add_f32 v[112:113], v[112:113], -1.0 op_sel_hi:[1,0]
	ds_bpermute_b32 v131, v183, v129
	s_nop 0
	v_pk_fma_f32 v[112:113], v[46:47], v[112:113], 1.0 op_sel_hi:[1,1,0]
	s_nop 0
	v_pk_mul_f32 v[112:113], v[112:113], v[216:217]
	s_nop 0
	v_pk_mul_f32 v[112:113], v[112:113], v[212:213]
	s_nop 0
	v_pk_mul_f32 v[112:113], v[42:43], v[112:113]
	s_nop 0
	v_add_f32_e32 v113, v112, v113
	s_waitcnt lgkmcnt(0)
	v_add_f32_e32 v112, v129, v131
	s_nop 0
	ds_bpermute_b32 v118, v184, v112
	s_nop 0
	s_nop 0
	s_nop 0
	s_nop 0
	s_waitcnt lgkmcnt(0)
	v_add_f32_e32 v129, v112, v118
	v_fmac_f32_e32 v174, 0xbc800000, v129
	v_fmac_f32_e32 v175, 0xbc800000, v129
	v_fmac_f32_e32 v177, 0xbc800000, v129
	v_fmac_f32_e32 v176, 0xbc800000, v129
	v_mov_b32_e32 v192, v177
	v_mov_b32_e32 v193, v175
	v_mov_b32_e32 v194, v176
	v_mov_b32_e32 v195, v174
	v_pk_mul_f32 v[192:193], v[192:193], v[192:193]
	v_pk_mul_f32 v[194:195], v[194:195], v[194:195]
	v_fmac_f32_e32 v156, 0xbc800000, v129
	v_pk_mov_b32 v[196:197], v[194:195], v[192:193] op_sel:[1,0]
	v_mov_b32_e32 v195, v193
	v_pk_add_f32 v[192:193], v[196:197], v[194:195]
	v_fmac_f32_e32 v157, 0xbc800000, v129
	v_mov_b32_e32 v196, v168
	v_fmamk_f32 v194, v129, 0xbc800000, v169
	v_mov_b32_e32 v195, v157
	v_fmac_f32_e32 v196, 0xbc800000, v129
	v_mov_b32_e32 v197, v156
	v_pk_mul_f32 v[194:195], v[194:195], v[194:195]
	v_pk_mul_f32 v[198:199], v[196:197], v[196:197]
	v_fmac_f32_e32 v144, 0xbc800000, v129
	v_pk_mov_b32 v[200:201], v[198:199], v[194:195] op_sel:[1,0]
	v_mov_b32_e32 v199, v195
	v_fmac_f32_e32 v140, 0xbc800000, v129
	v_fmac_f32_e32 v145, 0xbc800000, v129
	v_mul_f32_e32 v112, v144, v144
	v_pk_add_f32 v[194:195], v[200:201], v[198:199]
	v_fmac_f32_e32 v141, 0xbc800000, v129
	v_pk_fma_f32 v[198:199], v[144:145], v[144:145], v[112:113] op_sel_hi:[1,1,0]
	v_mul_f32_e32 v112, v140, v140
	v_pk_add_f32 v[192:193], v[192:193], v[192:193] op_sel_hi:[0,1]
	v_pk_add_f32 v[194:195], v[194:195], v[194:195] op_sel_hi:[0,1]
	v_pk_fma_f32 v[200:201], v[140:141], v[140:141], v[112:113] op_sel_hi:[1,1,0]
	v_fmac_f32_e32 v138, 0xbc800000, v129
	v_fmac_f32_e32 v136, 0xbc800000, v129
	v_fmac_f32_e32 v130, 0xbc800000, v129
	v_fmac_f32_e32 v128, 0xbc800000, v129
	v_mul_f32_e32 v198, v138, v138
	v_mul_f32_e32 v200, v136, v136
	v_mul_f32_e32 v192, v130, v130
	v_mul_f32_e32 v194, v128, v128
	v_pk_add_f32 v[198:199], v[198:199], v[200:201]
	v_pk_add_f32 v[192:193], v[192:193], v[194:195]
	s_nop 0
	v_pk_add_f32 v[192:193], v[198:199], v[192:193]
	s_nop 0
	v_add_f32_e32 v112, v192, v193
	ds_bpermute_b32 v118, v183, v112
	s_nop 0
	s_nop 0
	s_nop 0
	s_nop 0
	s_waitcnt lgkmcnt(0)
; __device__ __forceinline__ float fsigmoid(float x) { return __builtin_amdgcn_rcpf(1.0f + __expf(-x)); }
; __device__ __forceinline__ void gn_phase(bf16_t* Y, const bf16_t* R, const bf16_t* Kb, const bf16_t* V, const bf16_t* Z, const bf16_t* WA, const float* k_a, const float* r_k, const float* gn_g, const float* gn_b, int G, int bid, int tid) {
;     ...
;         s += __shfl_xor(s, 1); s += __shfl_xor(s, 2); bs += __shfl_xor(bs, 1); bs += __shfl_xor(bs, 2);
;         const float mean = s * (1.0f / 64.0f);
;         float q2 = 0.f;
; #pragma unroll
;         for (int q = 0; q < 4; ++q) { const f32x4 dlt = y[q] - mean; q2 += (dlt.x * dlt.x + dlt.y * dlt.y) + (dlt.z * dlt.z + dlt.w * dlt.w); }
;         q2 += __shfl_xor(q2, 1); q2 += __shfl_xor(q2, 2);
;         const float rstd = 1.0f / sqrtf(q2 * (1.0f / 64.0f) + 64e-5f);
;         f32x4 o[4];
; #pragma unroll
;         for (int q = 0; q < 4; ++q) {
;             const f32x4 yn = (y[q] - mean) * rstd * ggq[q] + gbq[q] + bs * v[q];
; #pragma unroll
;             for (int e = 0; e < 4; ++e) o[q][e] = yn[e] * z[q][e] * fsigmoid(z[q][e]);
	v_add_f32_e32 v131, v112, v118
	ds_bpermute_b32 v135, v184, v131
	s_nop 0
	s_nop 0
	s_nop 0
	s_nop 0
	s_nop 0
	s_nop 0
	s_nop 0
	s_nop 0
	s_nop 0
	s_waitcnt lgkmcnt(0)
	v_add_f32_e32 v114, v131, v135
	s_nop 0
	s_nop 0
	v_fmamk_f32 v114, v114, 0x3c800000, v161
	s_nop 0
	v_mul_f32_e32 v118, 0x4f800000, v114
	v_cmp_gt_f32_e32 vcc, s6, v114
	s_nop 0
	s_nop 0
	v_cndmask_b32_e32 v118, v114, v118, vcc
	v_sqrt_f32_e32 v119, v118
	s_nop 0
	s_nop 0
	s_nop 0
	v_add_u32_e32 v114, -1, v119
	v_fma_f32 v115, -v114, v119, v118
	v_cmp_ge_f32_e64 s[2:3], 0, v115
	v_add_u32_e32 v115, 1, v119
	s_nop 0
	v_cndmask_b32_e64 v114, v119, v114, s[2:3]
	v_fma_f32 v119, -v115, v119, v118
	v_cmp_lt_f32_e64 s[2:3], 0, v119
	s_nop 1
	v_cndmask_b32_e64 v114, v114, v115, s[2:3]
	v_mul_f32_e32 v115, 0x37800000, v114
	v_cndmask_b32_e32 v114, v114, v115, vcc
	v_cmp_class_f32_e32 vcc, v118, v182
	s_nop 1
	v_cndmask_b32_e32 v119, v114, v118, vcc
	v_div_scale_f32 v131, s[2:3], v119, v119, 1.0
	v_rcp_f32_e32 v135, v131
	s_nop 0
	v_mov_b32_e32 v114, 0
	ds_bpermute_b32 v118, v183, v114
	v_mul_f32_e32 v115, 0x3c800000, v129
	v_fma_f32 v112, -v131, v135, 1.0
	v_fmac_f32_e32 v135, v112, v135
	v_div_scale_f32 v112, vcc, 1.0, v119, 1.0
	v_mul_f32_e32 v113, v112, v135
	v_fma_f32 v129, -v131, v113, v112
	v_fmac_f32_e32 v113, v129, v135
	v_mul_f32_e32 v129, 0xbfb8aa3b, v147
	v_exp_f32_e32 v129, v129
	v_fma_f32 v112, -v131, v113, v112
	v_div_fmas_f32 v112, v112, v135, v113
	v_div_fixup_f32 v113, v112, v119, 1.0
	v_add_f32_e32 v112, 1.0, v129
	v_rcp_f32_e32 v129, v112
	v_mul_f32_e32 v112, 0xbfb8aa3b, v149
	v_exp_f32_e32 v112, v112
	v_mul_f32_e32 v119, 0xbfb8aa3b, v185
	v_exp_f32_e32 v119, v119
	v_mul_f32_e32 v173, v176, v113
	v_add_f32_e32 v112, 1.0, v112
	v_rcp_f32_e32 v131, v112
	v_add_f32_e32 v112, 1.0, v119
	v_rcp_f32_e32 v135, v112
	v_mul_f32_e32 v112, 0xbfb8aa3b, v226
	v_exp_f32_e32 v112, v112
	v_mul_f32_e32 v119, 0xbfb8aa3b, v227
	v_exp_f32_e32 v119, v119
	v_mul_f32_e32 v171, v174, v113
	v_add_f32_e32 v112, 1.0, v112
	v_rcp_f32_e32 v137, v112
	v_add_f32_e32 v112, 1.0, v119
	v_mov_b32_e32 v119, v169
	v_rcp_f32_e32 v139, v112
	v_mul_f32_e32 v112, 0xbfb8aa3b, v228
	s_waitcnt lgkmcnt(0)
	v_pk_add_f32 v[118:119], v[114:115], v[118:119]
	v_exp_f32_e32 v143, v112
	ds_bpermute_b32 v112, v184, v118
	v_pk_add_f32 v[168:169], v[168:169], v[114:115] neg_lo:[0,1] neg_hi:[0,1]
	v_mul_f32_e32 v159, v177, v113
	v_mul_f32_e32 v155, v175, v113
	v_mul_f32_e32 v151, v156, v113
	s_waitcnt lgkmcnt(0)
; __device__ __forceinline__ float fsigmoid(float x) { return __builtin_amdgcn_rcpf(1.0f + __expf(-x)); }
; __device__ __forceinline__ u32x4 pack8(const f32x4 a, const f32x4 b) { u32x4 w; w.x = cvt_pk_bf16(a[0], a[1]); w.y = cvt_pk_bf16(a[2], a[3]); w.z = cvt_pk_bf16(b[0], b[1]); w.w = cvt_pk_bf16(b[2], b[3]); return w; }
; __device__ __forceinline__ void gn_phase(bf16_t* Y, const bf16_t* R, const bf16_t* Kb, const bf16_t* V, const bf16_t* Z, const bf16_t* WA, const float* k_a, const float* r_k, const float* gn_g, const float* gn_b, int G, int bid, int tid) {
;     ...
;         for (int q = 0; q < 4; ++q) {
;             const f32x4 yn = (y[q] - mean) * rstd * ggq[q] + gbq[q] + bs * v[q];
; #pragma unroll
;             for (int e = 0; e < 4; ++e) o[q][e] = yn[e] * z[q][e] * fsigmoid(z[q][e]);
;         }
;         *(u32x4*)(Y + off) = pack8(o[0], o[1]); *(u32x4*)(Y + off + 8) = pack8(o[2], o[3]);
	s_nop 0
	v_mov_b32_e32 v114, v238
	v_pk_mul_f32 v[118:119], v[168:169], v[112:113]
	v_mul_f32_e32 v153, v196, v113
	v_mov_b32_e32 v115, v119
	v_mov_b32_e32 v118, v114
	v_mov_b32_e32 v119, v28
	v_pk_mul_f32 v[118:119], v[118:119], v[172:173]
	v_add_f32_e32 v143, 1.0, v143
	v_add_f32_e32 v112, v24, v119
	v_add_f32_e32 v112, v118, v112
	v_mov_b32_e32 v118, v114
	v_mov_b32_e32 v119, v29
	v_mul_f32_e32 v112, v112, v147
	v_pk_mul_f32 v[118:119], v[118:119], v[170:171]
	v_mul_f32_e32 v129, v129, v112
	v_add_f32_e32 v112, v25, v119
	v_add_f32_e32 v112, v118, v112
	v_mov_b32_e32 v118, v114
	v_mov_b32_e32 v119, v30
	v_mul_f32_e32 v112, v112, v149
	v_pk_mul_f32 v[118:119], v[118:119], v[158:159]
	v_mul_f32_e32 v131, v131, v112
	v_add_f32_e32 v112, v26, v119
	v_add_f32_e32 v112, v118, v112
	v_mov_b32_e32 v118, v114
	v_mov_b32_e32 v119, v31
	v_mul_f32_e32 v112, v112, v185
	v_pk_mul_f32 v[118:119], v[118:119], v[154:155]
	v_mul_f32_e32 v156, v135, v112
	v_add_f32_e32 v112, v27, v119
	v_add_f32_e32 v112, v118, v112
	v_mov_b32_e32 v118, v114
	v_mov_b32_e32 v119, v20
	v_mul_f32_e32 v112, v112, v226
	v_pk_mul_f32 v[118:119], v[118:119], v[152:153]
	v_mul_f32_e32 v137, v137, v112
	v_add_f32_e32 v112, v16, v119
	v_add_f32_e32 v112, v118, v112
	v_mov_b32_e32 v118, v114
	v_mov_b32_e32 v119, v21
	v_mul_f32_e32 v112, v112, v227
	v_pk_mul_f32 v[118:119], v[118:119], v[150:151]
	v_mul_f32_e32 v139, v139, v112
	v_add_f32_e32 v112, v17, v119
	v_add_f32_e32 v112, v118, v112
	v_mul_f32_e32 v118, 0xbfb8aa3b, v229
	v_rcp_f32_e32 v143, v143
	v_exp_f32_e32 v135, v118
	v_mul_f32_e32 v112, v112, v228
	v_pk_mul_f32 v[118:119], v[114:115], v[166:167]
	v_mul_f32_e32 v150, v143, v112
	v_add_f32_e32 v112, 1.0, v135
	v_rcp_f32_e32 v112, v112
	v_add_f32_e32 v115, v18, v119
	v_add_f32_e32 v115, v118, v115
	v_mul_f32_e32 v115, v115, v229
	v_mul_f32_e32 v151, v112, v115
	v_mul_f32_e32 v112, 0xbfb8aa3b, v230
	v_exp_f32_e32 v112, v112
	v_mul_f32_e32 v147, v157, v113
	v_mov_b32_e32 v115, v23
	v_pk_mul_f32 v[118:119], v[114:115], v[146:147]
	v_add_f32_e32 v112, 1.0, v112
	v_rcp_f32_e32 v112, v112
	v_add_f32_e32 v115, v19, v119
	v_add_f32_e32 v115, v118, v115
	v_mul_f32_e32 v115, v115, v230
	v_mul_f32_e32 v146, v112, v115
	v_mul_f32_e32 v112, 0xbfb8aa3b, v127
	v_exp_f32_e32 v112, v112
	v_mul_f32_e32 v149, v144, v113
	v_mov_b32_e32 v115, v12
	v_pk_mul_f32 v[118:119], v[114:115], v[148:149]
	v_add_f32_e32 v112, 1.0, v112
	v_rcp_f32_e32 v112, v112
	v_add_f32_e32 v115, v8, v119
	v_add_f32_e32 v115, v118, v115
	v_mul_f32_e32 v115, v115, v127
	v_mul_f32_e32 v144, v112, v115
	v_mul_f32_e32 v112, 0xbfb8aa3b, v133
	v_exp_f32_e32 v112, v112
	v_mul_f32_e32 v143, v145, v113
	v_mov_b32_e32 v115, v13
	v_pk_mul_f32 v[118:119], v[114:115], v[142:143]
	v_add_f32_e32 v112, 1.0, v112
	v_rcp_f32_e32 v112, v112
	v_add_f32_e32 v115, v9, v119
	v_add_f32_e32 v115, v118, v115
	v_mul_f32_e32 v115, v115, v133
	v_mul_f32_e32 v142, v112, v115
	v_mul_f32_e32 v112, 0xbfb8aa3b, v125
	v_exp_f32_e32 v112, v112
	v_mul_f32_e32 v135, v140, v113
	v_mov_b32_e32 v115, v14
	v_pk_mul_f32 v[118:119], v[114:115], v[134:135]
	v_add_f32_e32 v112, 1.0, v112
	v_rcp_f32_e32 v112, v112
	v_add_f32_e32 v115, v10, v119
	v_add_f32_e32 v115, v118, v115
	v_mul_f32_e32 v115, v115, v125
	v_mul_f32_e32 v134, v112, v115
	v_mul_f32_e32 v112, 0xbfb8aa3b, v123
	v_exp_f32_e32 v112, v112
	v_mul_f32_e32 v133, v141, v113
	v_mov_b32_e32 v115, v15
	v_pk_mul_f32 v[118:119], v[114:115], v[132:133]
	v_add_f32_e32 v112, 1.0, v112
	v_rcp_f32_e32 v112, v112
	v_add_f32_e32 v115, v11, v119
	v_add_f32_e32 v115, v118, v115
	v_mul_f32_e32 v115, v115, v123
	v_mul_f32_e32 v132, v112, v115
	v_mul_f32_e32 v112, 0xbfb8aa3b, v121
	v_exp_f32_e32 v112, v112
	v_mul_f32_e32 v127, v138, v113
	v_mov_b32_e32 v115, v4
	v_pk_mul_f32 v[118:119], v[114:115], v[126:127]
	v_add_f32_e32 v112, 1.0, v112
	v_rcp_f32_e32 v112, v112
	v_add_f32_e32 v115, v0, v119
	v_add_f32_e32 v115, v118, v115
	v_mul_f32_e32 v115, v115, v121
	v_mul_f32_e32 v126, v112, v115
	v_mul_f32_e32 v112, 0xbfb8aa3b, v117
	v_exp_f32_e32 v112, v112
	v_mul_f32_e32 v125, v136, v113
	v_mov_b32_e32 v115, v5
	v_pk_mul_f32 v[118:119], v[114:115], v[124:125]
	v_add_f32_e32 v112, 1.0, v112
	v_rcp_f32_e32 v112, v112
	v_add_f32_e32 v115, v1, v119
	v_add_f32_e32 v115, v118, v115
	v_mul_f32_e32 v115, v115, v117
	v_mul_f32_e32 v117, v112, v115
	v_mul_f32_e32 v112, 0xbfb8aa3b, v116
	v_exp_f32_e32 v112, v112
	v_mul_f32_e32 v123, v130, v113
	v_mov_b32_e32 v115, v6
	v_pk_mul_f32 v[118:119], v[114:115], v[122:123]
	v_add_f32_e32 v112, 1.0, v112
	v_rcp_f32_e32 v112, v112
	v_add_f32_e32 v115, v2, v119
	v_add_f32_e32 v115, v118, v115
	v_mul_f32_e32 v115, v115, v116
	v_mul_f32_e32 v116, v112, v115
	v_mul_f32_e32 v112, 0xbfb8aa3b, v22
	v_exp_f32_e32 v118, v112
	v_mul_f32_e32 v121, v128, v113
	v_mov_b32_e32 v115, v7
	v_pk_mul_f32 v[112:113], v[114:115], v[120:121]
	v_add_f32_e32 v114, 1.0, v118
	v_rcp_f32_e32 v114, v114
	v_add_f32_e32 v113, v3, v113
	v_add_f32_e32 v112, v112, v113
	v_mul_f32_e32 v22, v112, v22
	v_mul_f32_e32 v22, v114, v22
	v_cvt_pk_bf16_f32 v112, v129, v131
	v_cvt_pk_bf16_f32 v113, v156, v137
	v_cvt_pk_bf16_f32 v114, v139, v150
	v_cvt_pk_bf16_f32 v115, v151, v146
	global_store_dwordx4 v[164:165], v[112:115], off
	s_waitcnt vmcnt(1)
	v_mov_b64_e32 v[130:131], v[106:107]
	v_mov_b64_e32 v[138:139], v[98:99]
	v_cvt_pk_bf16_f32 v112, v144, v142
	v_cvt_pk_bf16_f32 v113, v134, v132
	v_cvt_pk_bf16_f32 v114, v126, v117
	v_cvt_pk_bf16_f32 v115, v116, v22
	global_store_dwordx4 v[164:165], v[112:115], off offset:16
	v_mov_b64_e32 v[118:119], v[102:103]
	v_mov_b64_e32 v[146:147], v[90:91]
	v_mov_b64_e32 v[114:115], v[110:111]
	v_mov_b64_e32 v[122:123], v[94:95]
	v_mov_b64_e32 v[150:151], v[82:83]
	v_mov_b64_e32 v[126:127], v[86:87]
	v_mov_b64_e32 v[154:155], v[74:75]
	v_mov_b64_e32 v[134:135], v[78:79]
	v_mov_b64_e32 v[158:159], v[66:67]
	v_mov_b64_e32 v[142:143], v[70:71]
	v_lshl_add_u64 v[164:165], v[164:165], 0, s[0:1]
	s_andn2_b64 vcc, exec, s[4:5]
	v_mov_b64_e32 v[128:129], v[104:105]
	v_mov_b64_e32 v[112:113], v[108:109]
	v_mov_b64_e32 v[136:137], v[96:97]
	v_mov_b64_e32 v[116:117], v[100:101]
	v_mov_b64_e32 v[144:145], v[88:89]
	v_mov_b64_e32 v[120:121], v[92:93]
	v_mov_b64_e32 v[148:149], v[80:81]
	v_mov_b64_e32 v[124:125], v[84:85]
	v_mov_b64_e32 v[152:153], v[72:73]
	v_mov_b64_e32 v[132:133], v[76:77]
	v_mov_b64_e32 v[156:157], v[64:65]
	v_mov_b64_e32 v[140:141], v[68:69]
	v_mov_b32_e32 v238, v239
	s_cbranch_vccz .LBB0_1012
